# FF2 residual epilogue: loads batched (3 row groups in flight), gate vectors loaded once per tile instead of 32 serialized load-wait-store steps
# speedup vs baseline: 1.0115x; 1.0115x over previous
; #define PG8_STAGE(bufoff, gbase, voff) do { _Pragma("unroll") for (int _i = 0; _i < 2; ++_i) \
;         __builtin_amdgcn_global_load_lds((const unsigned*)((const char*)(gbase) + (voff)[_i]), (LAS unsigned*)(lds + (bufoff) + ldsw + _i * 8192), 16, 0, 0); } while (0)
; #define PG8_LDA(dst, b, h) do { _Pragma("unroll") for (int m = 0; m < 4; ++m) _Pragma("unroll") for (int k = 0; k < 2; ++k) dst[m][k] = *(const LAS bf16x8*)(lds + PG8_SA(b, h) + aoff + m * 2048 + k * 1024); } while (0)
; #define PG8_LDB(dst, b, h) do { _Pragma("unroll") for (int n = 0; n < 2; ++n) _Pragma("unroll") for (int k = 0; k < 2; ++k) dst[n][k] = *(const LAS bf16x8*)(lds + PG8_SB(b, h) + boff + n * 2048 + k * 1024); } while (0)
; #define PG8_MMA(ai, bj, At, Bt) do { __builtin_amdgcn_s_setprio(1); _Pragma("unroll") for (int m = 0; m < 4; ++m) _Pragma("unroll") for (int n = 0; n < 2; ++n) _Pragma("unroll") for (int k = 0; k < 2; ++k) \
;         acc[ai][bj][m][n] = __builtin_amdgcn_mfma_f32_16x16x32_bf16(Bt[n][k], At[m][k], acc[ai][bj][m][n], 0, 0, 0); __builtin_amdgcn_s_setprio(0); } while (0)
; #define PG8_WAIT_L(n) asm volatile("s_waitcnt lgkmcnt(" #n ")" ::: "memory")
; #define PG8_BAR __builtin_amdgcn_s_barrier()
; #define PG8_SCHED __builtin_amdgcn_sched_barrier(0)
; template <class Epi, class Sched>
; __device__ __forceinline__ void gemm_phase(LAS unsigned char* lds, const Gemm g, const Sched& S, const Epi& E) {
;     ...
;             PG8_LDB(B0, 0, 0); PG8_SCHED; PG8_LDA(At, 0, 0); PG8_STAGE(PG8_SA(1, 1), a1 + hstep, voffA);
;             PG8_WAIT_L(8); PG8_BAR; PG8_WAIT_L(0); PG8_MMA(0, 0, At, B0); PG8_BAR; PG8_SCHED;
;             PG8_LDB(B1, 0, 1); PG8_STAGE(PG8_SB(0, 0), b2, voffB);
;             PG8_BAR; PG8_WAIT_L(0); PG8_MMA(0, 1, At, B1); PG8_BAR;
;             PG8_LDA(At, 0, 1); PG8_STAGE(PG8_SA(0, 0), a2, voffA);
;             PG8_BAR; PG8_WAIT_L(0); PG8_MMA(1, 0, At, B0); PG8_BAR; PG8_SCHED;
.LBB0_1343:
	s_nop 0
	v_add_u32_e32 v136, s42, v139
	ds_read_b128 v[142:145], v136
	ds_read_b128 v[146:149], v136 offset:1024
	ds_read_b128 v[150:153], v136 offset:2048
	ds_read_b128 v[154:157], v136 offset:3072
	s_add_u32 s18, s16, 0x100
	s_addc_u32 s19, s17, 0
	s_cmpk_eq_i32 s40, 0x7c
	s_cselect_b32 s23, s3, s19
	s_cselect_b32 s22, s7, s18
	s_cselect_b32 s21, s5, s39
	s_cselect_b32 s20, s37, s38
	v_lshl_add_u64 v[136:137], s[16:17], 0, v[132:133]
	s_add_i32 m0, s13, 0xc000
	ds_read_b128 v[158:161], v141
	ds_read_b128 v[162:165], v141 offset:1024
	ds_read_b128 v[166:169], v141 offset:2048
	ds_read_b128 v[170:173], v141 offset:3072
	ds_read_b128 v[174:177], v141 offset:4096
	ds_read_b128 v[178:181], v141 offset:5120
	ds_read_b128 v[182:185], v141 offset:6144
	ds_read_b128 v[186:189], v141 offset:7168
	global_load_lds_dwordx4 v[136:137], off
	v_lshl_add_u64 v[136:137], s[16:17], 0, v[134:135]
	s_add_i32 m0, s13, 0xe000
	s_nop 0
	global_load_lds_dwordx4 v[136:137], off
	s_waitcnt lgkmcnt(8)
	s_barrier
	s_waitcnt lgkmcnt(0)
	s_setprio 1
	s_waitcnt lgkmcnt(0)
	v_mfma_f32_16x16x32_bf16 v[126:129], v[142:145], v[158:161], v[126:129]
	v_mfma_f32_16x16x32_bf16 v[122:125], v[150:153], v[158:161], v[122:125]
	v_mfma_f32_16x16x32_bf16 v[110:113], v[142:145], v[166:169], v[110:113]
	v_mfma_f32_16x16x32_bf16 v[106:109], v[150:153], v[166:169], v[106:109]
	v_mfma_f32_16x16x32_bf16 v[94:97], v[142:145], v[174:177], v[94:97]
	v_mfma_f32_16x16x32_bf16 v[90:93], v[150:153], v[174:177], v[90:93]
	v_mfma_f32_16x16x32_bf16 v[78:81], v[142:145], v[182:185], v[78:81]
	v_mfma_f32_16x16x32_bf16 v[74:77], v[150:153], v[182:185], v[74:77]
	v_mfma_f32_16x16x32_bf16 v[126:129], v[146:149], v[162:165], v[126:129]
	v_mfma_f32_16x16x32_bf16 v[122:125], v[154:157], v[162:165], v[122:125]
	v_mfma_f32_16x16x32_bf16 v[110:113], v[146:149], v[170:173], v[110:113]
	v_mfma_f32_16x16x32_bf16 v[106:109], v[154:157], v[170:173], v[106:109]
	v_mfma_f32_16x16x32_bf16 v[94:97], v[146:149], v[178:181], v[94:97]
	v_mfma_f32_16x16x32_bf16 v[90:93], v[154:157], v[178:181], v[90:93]
	v_mfma_f32_16x16x32_bf16 v[78:81], v[146:149], v[186:189], v[78:81]
	v_mfma_f32_16x16x32_bf16 v[74:77], v[154:157], v[186:189], v[74:77]
	s_setprio 0
	s_barrier
	s_add_i32 s41, 0, 0x14000
	v_add_u32_e32 v136, s41, v139
	s_add_i32 s16, s42, s28
	ds_read_b128 v[190:193], v136
	ds_read_b128 v[194:197], v136 offset:1024
	ds_read_b128 v[198:201], v136 offset:2048
	ds_read_b128 v[202:205], v136 offset:3072
	v_lshl_add_u64 v[136:137], s[20:21], 0, v[0:1]
	s_mov_b32 m0, s16
	v_lshl_add_u64 v[206:207], s[20:21], 0, v[130:131]
	global_load_lds_dwordx4 v[136:137], off
	s_add_i32 m0, s16, 0x2000
	s_nop 0
	global_load_lds_dwordx4 v[206:207], off
	s_barrier
	s_waitcnt lgkmcnt(0)
	s_setprio 1
	s_waitcnt lgkmcnt(0)
	v_mfma_f32_16x16x32_bf16 v[118:121], v[190:193], v[158:161], v[118:121]
	v_mfma_f32_16x16x32_bf16 v[114:117], v[198:201], v[158:161], v[114:117]
	v_mfma_f32_16x16x32_bf16 v[102:105], v[190:193], v[166:169], v[102:105]
	v_mfma_f32_16x16x32_bf16 v[98:101], v[198:201], v[166:169], v[98:101]
	v_mfma_f32_16x16x32_bf16 v[86:89], v[190:193], v[174:177], v[86:89]
	v_mfma_f32_16x16x32_bf16 v[82:85], v[198:201], v[174:177], v[82:85]
	v_mfma_f32_16x16x32_bf16 v[70:73], v[190:193], v[182:185], v[70:73]
	v_mfma_f32_16x16x32_bf16 v[66:69], v[198:201], v[182:185], v[66:69]
	v_mfma_f32_16x16x32_bf16 v[118:121], v[194:197], v[162:165], v[118:121]
	v_mfma_f32_16x16x32_bf16 v[114:117], v[202:205], v[162:165], v[114:117]
	v_mfma_f32_16x16x32_bf16 v[102:105], v[194:197], v[170:173], v[102:105]
	v_mfma_f32_16x16x32_bf16 v[98:101], v[202:205], v[170:173], v[98:101]
	v_mfma_f32_16x16x32_bf16 v[86:89], v[194:197], v[178:181], v[86:89]
	v_mfma_f32_16x16x32_bf16 v[82:85], v[202:205], v[178:181], v[82:85]
	v_mfma_f32_16x16x32_bf16 v[70:73], v[194:197], v[186:189], v[70:73]
	v_mfma_f32_16x16x32_bf16 v[66:69], v[202:205], v[186:189], v[66:69]
	s_setprio 0
	s_mov_b32 m0, s13
	v_lshl_add_u64 v[208:209], s[22:23], 0, v[0:1]
	s_barrier
	ds_read_b128 v[158:161], v141 offset:16384
	ds_read_b128 v[162:165], v141 offset:17408
	ds_read_b128 v[166:169], v141 offset:18432
	ds_read_b128 v[170:173], v141 offset:19456
	ds_read_b128 v[174:177], v141 offset:20480
	ds_read_b128 v[178:181], v141 offset:21504
	ds_read_b128 v[182:185], v141 offset:22528
	ds_read_b128 v[186:189], v141 offset:23552
	global_load_lds_dwordx4 v[208:209], off
	v_lshl_add_u64 v[210:211], s[22:23], 0, v[130:131]
	s_mov_b32 m0, s15
	s_nop 0
	global_load_lds_dwordx4 v[210:211], off
	s_barrier
	s_waitcnt lgkmcnt(0)
	s_setprio 1
	s_waitcnt lgkmcnt(0)
	v_mfma_f32_16x16x32_bf16 v[62:65], v[142:145], v[158:161], v[62:65]
	v_mfma_f32_16x16x32_bf16 v[58:61], v[150:153], v[158:161], v[58:61]
	v_mfma_f32_16x16x32_bf16 v[46:49], v[142:145], v[166:169], v[46:49]
	v_mfma_f32_16x16x32_bf16 v[42:45], v[150:153], v[166:169], v[42:45]
	v_mfma_f32_16x16x32_bf16 v[30:33], v[142:145], v[174:177], v[30:33]
	v_mfma_f32_16x16x32_bf16 v[26:29], v[150:153], v[174:177], v[26:29]
	v_mfma_f32_16x16x32_bf16 v[14:17], v[142:145], v[182:185], v[14:17]
	v_mfma_f32_16x16x32_bf16 v[10:13], v[150:153], v[182:185], v[10:13]
	v_mfma_f32_16x16x32_bf16 v[62:65], v[146:149], v[162:165], v[62:65]
	v_mfma_f32_16x16x32_bf16 v[58:61], v[154:157], v[162:165], v[58:61]
	v_mfma_f32_16x16x32_bf16 v[46:49], v[146:149], v[170:173], v[46:49]
	v_mfma_f32_16x16x32_bf16 v[42:45], v[154:157], v[170:173], v[42:45]
	v_mfma_f32_16x16x32_bf16 v[30:33], v[146:149], v[178:181], v[30:33]
	v_mfma_f32_16x16x32_bf16 v[26:29], v[154:157], v[178:181], v[26:29]
	v_mfma_f32_16x16x32_bf16 v[14:17], v[146:149], v[186:189], v[14:17]
	v_mfma_f32_16x16x32_bf16 v[10:13], v[154:157], v[186:189], v[10:13]
	s_setprio 0
	s_barrier
; #define PG8_STAGE(bufoff, gbase, voff) do { _Pragma("unroll") for (int _i = 0; _i < 2; ++_i) \
;         __builtin_amdgcn_global_load_lds((const unsigned*)((const char*)(gbase) + (voff)[_i]), (LAS unsigned*)(lds + (bufoff) + ldsw + _i * 8192), 16, 0, 0); } while (0)
; #define PG8_LDA(dst, b, h) do { _Pragma("unroll") for (int m = 0; m < 4; ++m) _Pragma("unroll") for (int k = 0; k < 2; ++k) dst[m][k] = *(const LAS bf16x8*)(lds + PG8_SA(b, h) + aoff + m * 2048 + k * 1024); } while (0)
; #define PG8_LDB(dst, b, h) do { _Pragma("unroll") for (int n = 0; n < 2; ++n) _Pragma("unroll") for (int k = 0; k < 2; ++k) dst[n][k] = *(const LAS bf16x8*)(lds + PG8_SB(b, h) + boff + n * 2048 + k * 1024); } while (0)
; #define PG8_MMA(ai, bj, At, Bt) do { __builtin_amdgcn_s_setprio(1); _Pragma("unroll") for (int m = 0; m < 4; ++m) _Pragma("unroll") for (int n = 0; n < 2; ++n) _Pragma("unroll") for (int k = 0; k < 2; ++k) \
;         acc[ai][bj][m][n] = __builtin_amdgcn_mfma_f32_16x16x32_bf16(Bt[n][k], At[m][k], acc[ai][bj][m][n], 0, 0, 0); __builtin_amdgcn_s_setprio(0); } while (0)
; #define PG8_WAIT_V(n) asm volatile("s_waitcnt vmcnt(" #n ")" ::: "memory")
; #define PG8_WAIT_L(n) asm volatile("s_waitcnt lgkmcnt(" #n ")" ::: "memory")
; #define PG8_BAR __builtin_amdgcn_s_barrier()
; #define PG8_SCHED __builtin_amdgcn_sched_barrier(0)
; template <class Epi, class Sched>
; __device__ __forceinline__ void gemm_phase(LAS unsigned char* lds, const Gemm g, const Sched& S, const Epi& E) {
;     ...
;             PG8_STAGE(PG8_SB(0, 1), b2 + hstep, voffB);
;             PG8_WAIT_V(6); PG8_BAR; PG8_MMA(1, 1, At, B1); PG8_BAR;
;             PG8_LDB(B0, 1, 0); PG8_SCHED; PG8_LDA(At, 1, 0); PG8_STAGE(PG8_SA(0, 1), a2 + hstep, voffA);
;             PG8_WAIT_L(8); PG8_BAR; PG8_WAIT_L(0); PG8_MMA(0, 0, At, B0); PG8_BAR; PG8_SCHED;
;             PG8_LDB(B1, 1, 1); PG8_STAGE(PG8_SB(1, 0), b3, voffB);
;             PG8_BAR; PG8_WAIT_L(0); PG8_MMA(0, 1, At, B1); PG8_BAR;
;             PG8_LDA(At, 1, 1); PG8_STAGE(PG8_SA(1, 0), a3, voffA);
	s_add_u32 s16, s20, 0x200000
	s_addc_u32 s17, s21, 0
	s_add_i32 s41, s41, s28
	v_lshl_add_u64 v[142:143], s[16:17], 0, v[0:1]
	s_mov_b32 m0, s41
	s_nop 0
	global_load_lds_dwordx4 v[142:143], off
	v_lshl_add_u64 v[142:143], s[16:17], 0, v[130:131]
	s_add_i32 m0, s41, 0x2000
	s_nop 0
	global_load_lds_dwordx4 v[142:143], off
	s_waitcnt vmcnt(6)
	s_barrier
	s_setprio 1
	v_mfma_f32_16x16x32_bf16 v[54:57], v[190:193], v[158:161], v[54:57]
	v_mfma_f32_16x16x32_bf16 v[50:53], v[198:201], v[158:161], v[50:53]
	v_mfma_f32_16x16x32_bf16 v[38:41], v[190:193], v[166:169], v[38:41]
	v_mfma_f32_16x16x32_bf16 v[34:37], v[198:201], v[166:169], v[34:37]
	v_mfma_f32_16x16x32_bf16 v[22:25], v[190:193], v[174:177], v[22:25]
	v_mfma_f32_16x16x32_bf16 v[18:21], v[198:201], v[174:177], v[18:21]
	v_mfma_f32_16x16x32_bf16 v[6:9], v[190:193], v[182:185], v[6:9]
	v_mfma_f32_16x16x32_bf16 v[2:5], v[198:201], v[182:185], v[2:5]
	v_mfma_f32_16x16x32_bf16 v[54:57], v[194:197], v[162:165], v[54:57]
	v_mfma_f32_16x16x32_bf16 v[50:53], v[202:205], v[162:165], v[50:53]
	v_mfma_f32_16x16x32_bf16 v[38:41], v[194:197], v[170:173], v[38:41]
	v_mfma_f32_16x16x32_bf16 v[34:37], v[202:205], v[170:173], v[34:37]
	v_mfma_f32_16x16x32_bf16 v[22:25], v[194:197], v[178:181], v[22:25]
	v_mfma_f32_16x16x32_bf16 v[18:21], v[202:205], v[178:181], v[18:21]
	v_mfma_f32_16x16x32_bf16 v[6:9], v[194:197], v[186:189], v[6:9]
	v_mfma_f32_16x16x32_bf16 v[2:5], v[202:205], v[186:189], v[2:5]
	s_setprio 0
	s_add_i32 s41, 0, 0x18000
	v_add_u32_e32 v154, s41, v139
	s_barrier
	ds_read_b128 v[142:145], v154
	ds_read_b128 v[146:149], v154 offset:1024
	ds_read_b128 v[150:153], v154 offset:2048
	ds_read_b128 v[154:157], v154 offset:3072
	s_add_u32 s16, s22, 0x200000
	s_addc_u32 s17, s23, 0
	s_mov_b32 m0, s29
	v_lshl_add_u64 v[190:191], s[16:17], 0, v[0:1]
	ds_read_b128 v[158:161], v141 offset:32768
	ds_read_b128 v[162:165], v141 offset:33792
	ds_read_b128 v[166:169], v141 offset:34816
	ds_read_b128 v[170:173], v141 offset:35840
	ds_read_b128 v[174:177], v141 offset:36864
	ds_read_b128 v[178:181], v141 offset:37888
	ds_read_b128 v[182:185], v141 offset:38912
	ds_read_b128 v[186:189], v141 offset:39936
	global_load_lds_dwordx4 v[190:191], off
	v_lshl_add_u64 v[190:191], s[16:17], 0, v[130:131]
	s_mov_b32 m0, s30
	s_nop 0
	global_load_lds_dwordx4 v[190:191], off
	s_waitcnt lgkmcnt(8)
	s_barrier
	s_waitcnt lgkmcnt(0)
	s_setprio 1
	s_waitcnt lgkmcnt(0)
	v_mfma_f32_16x16x32_bf16 v[126:129], v[142:145], v[158:161], v[126:129]
	v_mfma_f32_16x16x32_bf16 v[122:125], v[150:153], v[158:161], v[122:125]
	v_mfma_f32_16x16x32_bf16 v[110:113], v[142:145], v[166:169], v[110:113]
	v_mfma_f32_16x16x32_bf16 v[106:109], v[150:153], v[166:169], v[106:109]
	v_mfma_f32_16x16x32_bf16 v[94:97], v[142:145], v[174:177], v[94:97]
	v_mfma_f32_16x16x32_bf16 v[90:93], v[150:153], v[174:177], v[90:93]
	v_mfma_f32_16x16x32_bf16 v[78:81], v[142:145], v[182:185], v[78:81]
	v_mfma_f32_16x16x32_bf16 v[74:77], v[150:153], v[182:185], v[74:77]
	v_mfma_f32_16x16x32_bf16 v[126:129], v[146:149], v[162:165], v[126:129]
	v_mfma_f32_16x16x32_bf16 v[122:125], v[154:157], v[162:165], v[122:125]
	v_mfma_f32_16x16x32_bf16 v[110:113], v[146:149], v[170:173], v[110:113]
	v_mfma_f32_16x16x32_bf16 v[106:109], v[154:157], v[170:173], v[106:109]
	v_mfma_f32_16x16x32_bf16 v[94:97], v[146:149], v[178:181], v[94:97]
	v_mfma_f32_16x16x32_bf16 v[90:93], v[154:157], v[178:181], v[90:93]
	v_mfma_f32_16x16x32_bf16 v[78:81], v[146:149], v[186:189], v[78:81]
	v_mfma_f32_16x16x32_bf16 v[74:77], v[154:157], v[186:189], v[74:77]
	s_setprio 0
	s_barrier
	s_add_i32 s22, 0, 0x1c000
	s_add_i32 s16, s41, s28
	v_add_u32_e32 v202, s22, v139
	v_lshl_add_u64 v[136:137], v[136:137], 0, s[44:45]
	s_mov_b32 m0, s16
	ds_read_b128 v[190:193], v202
	ds_read_b128 v[194:197], v202 offset:1024
	ds_read_b128 v[198:201], v202 offset:2048
	ds_read_b128 v[202:205], v202 offset:3072
	global_load_lds_dwordx4 v[136:137], off
	v_lshl_add_u64 v[136:137], v[206:207], 0, s[44:45]
	s_add_i32 m0, s16, 0x2000
	s_nop 0
	global_load_lds_dwordx4 v[136:137], off
	s_barrier
	s_waitcnt lgkmcnt(0)
	s_setprio 1
	s_waitcnt lgkmcnt(0)
	v_mfma_f32_16x16x32_bf16 v[118:121], v[190:193], v[158:161], v[118:121]
	v_mfma_f32_16x16x32_bf16 v[114:117], v[198:201], v[158:161], v[114:117]
	v_mfma_f32_16x16x32_bf16 v[102:105], v[190:193], v[166:169], v[102:105]
	v_mfma_f32_16x16x32_bf16 v[98:101], v[198:201], v[166:169], v[98:101]
	v_mfma_f32_16x16x32_bf16 v[86:89], v[190:193], v[174:177], v[86:89]
	v_mfma_f32_16x16x32_bf16 v[82:85], v[198:201], v[174:177], v[82:85]
	v_mfma_f32_16x16x32_bf16 v[70:73], v[190:193], v[182:185], v[70:73]
	v_mfma_f32_16x16x32_bf16 v[66:69], v[198:201], v[182:185], v[66:69]
	v_mfma_f32_16x16x32_bf16 v[118:121], v[194:197], v[162:165], v[118:121]
	v_mfma_f32_16x16x32_bf16 v[114:117], v[202:205], v[162:165], v[114:117]
	v_mfma_f32_16x16x32_bf16 v[102:105], v[194:197], v[170:173], v[102:105]
	v_mfma_f32_16x16x32_bf16 v[98:101], v[202:205], v[170:173], v[98:101]
	v_mfma_f32_16x16x32_bf16 v[86:89], v[194:197], v[178:181], v[86:89]
	v_mfma_f32_16x16x32_bf16 v[82:85], v[202:205], v[178:181], v[82:85]
	v_mfma_f32_16x16x32_bf16 v[70:73], v[194:197], v[186:189], v[70:73]
	v_mfma_f32_16x16x32_bf16 v[66:69], v[202:205], v[186:189], v[66:69]
	s_setprio 0
	s_mov_b32 m0, s34
	v_lshl_add_u64 v[136:137], v[208:209], 0, s[44:45]
	s_barrier
	ds_read_b128 v[158:161], v141 offset:49152
	ds_read_b128 v[162:165], v141 offset:50176
	ds_read_b128 v[166:169], v141 offset:51200
	ds_read_b128 v[170:173], v141 offset:52224
	ds_read_b128 v[174:177], v141 offset:53248
	ds_read_b128 v[178:181], v141 offset:54272
	ds_read_b128 v[182:185], v141 offset:55296
	ds_read_b128 v[186:189], v141 offset:56320
	global_load_lds_dwordx4 v[136:137], off
	v_lshl_add_u64 v[136:137], v[210:211], 0, s[44:45]
	s_mov_b32 m0, s35
	s_nop 0
	global_load_lds_dwordx4 v[136:137], off
	s_barrier
; #define PG8_STAGE(bufoff, gbase, voff) do { _Pragma("unroll") for (int _i = 0; _i < 2; ++_i) \
;         __builtin_amdgcn_global_load_lds((const unsigned*)((const char*)(gbase) + (voff)[_i]), (LAS unsigned*)(lds + (bufoff) + ldsw + _i * 8192), 16, 0, 0); } while (0)
; #define PG8_MMA(ai, bj, At, Bt) do { __builtin_amdgcn_s_setprio(1); _Pragma("unroll") for (int m = 0; m < 4; ++m) _Pragma("unroll") for (int n = 0; n < 2; ++n) _Pragma("unroll") for (int k = 0; k < 2; ++k) \
;         acc[ai][bj][m][n] = __builtin_amdgcn_mfma_f32_16x16x32_bf16(Bt[n][k], At[m][k], acc[ai][bj][m][n], 0, 0, 0); __builtin_amdgcn_s_setprio(0); } while (0)
; #define PG8_WAIT_V(n) asm volatile("s_waitcnt vmcnt(" #n ")" ::: "memory")
; #define PG8_WAIT_L(n) asm volatile("s_waitcnt lgkmcnt(" #n ")" ::: "memory")
; template <class Epi, class Sched>
; __device__ __forceinline__ void gemm_phase(LAS unsigned char* lds, const Gemm g, const Sched& S, const Epi& E) {
;     ...
;             PG8_BAR; PG8_WAIT_L(0); PG8_MMA(1, 0, At, B0); PG8_BAR; PG8_SCHED;
;             PG8_STAGE(PG8_SB(1, 1), b3 + hstep, voffB);
;             PG8_WAIT_V(6); PG8_BAR; PG8_MMA(1, 1, At, B1); PG8_BAR;
;         }
;         E(acc, cur, wr, wc, fr, fq); S.done(cur);
;         if (!has_next) break;
;     __device__ __forceinline__ void operator()(const f32x4 (&acc)[2][2][4][2], const pg8::Unit& u, int wr, int wc, int fr, int fq) const {
;         const int row0 = u.pm * 256 + wr * 64 + fr; const int col0 = u.pn * 256 + wc * 32 + 4 * fq;
; #pragma unroll
;         for (int ai = 0; ai < 2; ++ai)
; #pragma unroll
;             for (int m = 0; m < 4; ++m) { const int row = row0 + ai * 128 + m * 16;
;                 const float* ip; float* op; int b;
;                 if (row < ML_ROWS) { b = row >> 11; ip = xi + (size_t)row * D; op = xo + (size_t)row * D; }
;                 else { b = 8; ip = ci + (size_t)(row - ML_ROWS) * D; op = co + (size_t)(row - ML_ROWS) * D; }
;                 const float* gp = mod + (size_t)b * 12288 + slot * 2048;
; #pragma unroll
;                 for (int bj = 0; bj < 2; ++bj)
; #pragma unroll
;                     for (int n = 0; n < 2; ++n) { const int c = col0 + bj * 128 + n * 16;
;                         const f32x4 r = *(const f32x4*)(ip + c), g = *(const f32x4*)(gp + c);
;                         *(f32x4*)(op + c) = r + g * acc[ai][bj][m][n]; } }
	s_waitcnt lgkmcnt(0)
	s_setprio 1
	s_waitcnt lgkmcnt(0)
	v_mfma_f32_16x16x32_bf16 v[62:65], v[142:145], v[158:161], v[62:65]
	v_mfma_f32_16x16x32_bf16 v[58:61], v[150:153], v[158:161], v[58:61]
	v_mfma_f32_16x16x32_bf16 v[46:49], v[142:145], v[166:169], v[46:49]
	v_mfma_f32_16x16x32_bf16 v[42:45], v[150:153], v[166:169], v[42:45]
	v_mfma_f32_16x16x32_bf16 v[30:33], v[142:145], v[174:177], v[30:33]
	v_mfma_f32_16x16x32_bf16 v[26:29], v[150:153], v[174:177], v[26:29]
	v_mfma_f32_16x16x32_bf16 v[14:17], v[142:145], v[182:185], v[14:17]
	v_mfma_f32_16x16x32_bf16 v[10:13], v[150:153], v[182:185], v[10:13]
	v_mfma_f32_16x16x32_bf16 v[62:65], v[146:149], v[162:165], v[62:65]
	v_mfma_f32_16x16x32_bf16 v[58:61], v[154:157], v[162:165], v[58:61]
	v_mfma_f32_16x16x32_bf16 v[46:49], v[146:149], v[170:173], v[46:49]
	v_mfma_f32_16x16x32_bf16 v[42:45], v[154:157], v[170:173], v[42:45]
	v_mfma_f32_16x16x32_bf16 v[30:33], v[146:149], v[178:181], v[30:33]
	v_mfma_f32_16x16x32_bf16 v[26:29], v[154:157], v[178:181], v[26:29]
	v_mfma_f32_16x16x32_bf16 v[14:17], v[146:149], v[186:189], v[14:17]
	v_mfma_f32_16x16x32_bf16 v[10:13], v[154:157], v[186:189], v[10:13]
	s_setprio 0
	s_barrier
	s_add_u32 s16, s20, 0x200080
	s_addc_u32 s17, s21, 0
	s_add_i32 s20, s22, s28
	v_lshl_add_u64 v[136:137], s[16:17], 0, v[0:1]
	s_mov_b32 m0, s20
	s_nop 0
	global_load_lds_dwordx4 v[136:137], off
	v_lshl_add_u64 v[136:137], s[16:17], 0, v[130:131]
	s_add_i32 m0, s20, 0x2000
	s_nop 0
	global_load_lds_dwordx4 v[136:137], off
	s_waitcnt vmcnt(6)
	s_barrier
	s_setprio 1
	v_mfma_f32_16x16x32_bf16 v[54:57], v[190:193], v[158:161], v[54:57]
	v_mfma_f32_16x16x32_bf16 v[50:53], v[198:201], v[158:161], v[50:53]
	v_mfma_f32_16x16x32_bf16 v[38:41], v[190:193], v[166:169], v[38:41]
	v_mfma_f32_16x16x32_bf16 v[34:37], v[198:201], v[166:169], v[34:37]
	v_mfma_f32_16x16x32_bf16 v[22:25], v[190:193], v[174:177], v[22:25]
	v_mfma_f32_16x16x32_bf16 v[18:21], v[198:201], v[174:177], v[18:21]
	v_mfma_f32_16x16x32_bf16 v[6:9], v[190:193], v[182:185], v[6:9]
	v_mfma_f32_16x16x32_bf16 v[2:5], v[198:201], v[182:185], v[2:5]
	v_mfma_f32_16x16x32_bf16 v[54:57], v[194:197], v[162:165], v[54:57]
	v_mfma_f32_16x16x32_bf16 v[50:53], v[202:205], v[162:165], v[50:53]
	v_mfma_f32_16x16x32_bf16 v[38:41], v[194:197], v[170:173], v[38:41]
	v_mfma_f32_16x16x32_bf16 v[34:37], v[202:205], v[170:173], v[34:37]
	v_mfma_f32_16x16x32_bf16 v[22:25], v[194:197], v[178:181], v[22:25]
	v_mfma_f32_16x16x32_bf16 v[18:21], v[202:205], v[178:181], v[18:21]
	v_mfma_f32_16x16x32_bf16 v[6:9], v[194:197], v[186:189], v[6:9]
	v_mfma_f32_16x16x32_bf16 v[2:5], v[202:205], v[186:189], v[2:5]
	s_setprio 0
	s_add_i32 s40, s40, 2
	s_add_u32 s38, s38, 0x100
	s_addc_u32 s39, s39, 0
	s_cmpk_gt_u32 s40, 0x7d
	s_mov_b64 s[16:17], s[18:19]
	s_barrier
	s_cbranch_scc0 .LBB0_1343
	s_lshl_b32 s3, s14, 8
	s_add_i32 s3, s3, s31
	v_readlane_b32 s40, v251, 0
	v_readlane_b32 s41, v251, 1
	v_readlane_b32 s42, v251, 2
	v_readlane_b32 s43, v251, 3
	v_readlane_b32 s44, v251, 4
	v_readlane_b32 s45, v251, 5
	v_readlane_b32 s46, v251, 6
	v_readlane_b32 s47, v251, 7
	v_readlane_b32 s18, v254, 2
	v_readlane_b32 s19, v254, 3
	s_add_i32 s5, s3, 0xffffc000
	s_ashr_i32 s7, s3, 11
	s_cmpk_lt_i32 s3, 0x4000
	s_cselect_b32 s20, s42, s60
	s_cselect_b32 s21, s43, s61
	s_cselect_b32 s5, s3, s5
	s_cselect_b32 s7, s7, 8
	s_mul_i32 s7, s7, 0xc000
	s_add_u32 s18, s18, s7
	s_addc_u32 s19, s19, 0
	s_add_u32 s18, s18, 0xa000
	s_addc_u32 s19, s19, 0
	v_add_u32_e32 v136, s5, v138
	v_lshl_or_b32 v137, s12, 8, v140
	v_lshlrev_b32_e32 v137, 2, v137
	v_lshl_or_b32 v136, v136, 13, v137
	s_mov_b32 s12, s4
	s_mov_b32 s14, s6
	v_add_u32_e32 v142, 0x20000, v136
	v_add_u32_e32 v143, 0x40000, v136
	v_add_u32_e32 v144, 0x60000, v136
	v_add_u32_e32 v145, 0x100000, v136
	v_add_u32_e32 v210, 0x120000, v136
	v_add_u32_e32 v211, 0x140000, v136
	global_load_dwordx4 v[146:149], v137, s[18:19]
	global_load_dwordx4 v[150:153], v137, s[18:19] offset:64
	global_load_dwordx4 v[154:157], v137, s[18:19] offset:512
	global_load_dwordx4 v[158:161], v137, s[18:19] offset:576
	v_add_u32_e32 v137, 0x160000, v136
	global_load_dwordx4 v[162:165], v136, s[20:21]
	global_load_dwordx4 v[166:169], v136, s[20:21] offset:64
	global_load_dwordx4 v[170:173], v136, s[20:21] offset:512
	global_load_dwordx4 v[174:177], v136, s[20:21] offset:576
	global_load_dwordx4 v[178:181], v142, s[20:21]
	global_load_dwordx4 v[182:185], v142, s[20:21] offset:64
	global_load_dwordx4 v[186:189], v142, s[20:21] offset:512
	global_load_dwordx4 v[190:193], v142, s[20:21] offset:576
	global_load_dwordx4 v[194:197], v143, s[20:21]
	global_load_dwordx4 v[198:201], v143, s[20:21] offset:64
	global_load_dwordx4 v[202:205], v143, s[20:21] offset:512
	global_load_dwordx4 v[206:209], v143, s[20:21] offset:576
	s_waitcnt vmcnt(8)
	v_pk_fma_f32 v[126:127], v[126:127], v[146:147], v[162:163]
	v_pk_fma_f32 v[128:129], v[128:129], v[148:149], v[164:165]
	v_pk_fma_f32 v[122:123], v[122:123], v[150:151], v[166:167]
	v_pk_fma_f32 v[124:125], v[124:125], v[152:153], v[168:169]
	v_pk_fma_f32 v[118:119], v[118:119], v[154:155], v[170:171]
	v_pk_fma_f32 v[120:121], v[120:121], v[156:157], v[172:173]
	v_pk_fma_f32 v[114:115], v[114:115], v[158:159], v[174:175]
	v_pk_fma_f32 v[116:117], v[116:117], v[160:161], v[176:177]
	global_store_dwordx4 v136, v[126:129], s[20:21]
	global_store_dwordx4 v136, v[122:125], s[20:21] offset:64
	global_store_dwordx4 v136, v[118:121], s[20:21] offset:512
	global_store_dwordx4 v136, v[114:117], s[20:21] offset:576
	global_load_dwordx4 v[162:165], v144, s[20:21]
	global_load_dwordx4 v[166:169], v144, s[20:21] offset:64
	global_load_dwordx4 v[170:173], v144, s[20:21] offset:512
	global_load_dwordx4 v[174:177], v144, s[20:21] offset:576
	s_waitcnt vmcnt(12)
; template <class Epi, class Sched>
; __device__ __forceinline__ void gemm_phase(LAS unsigned char* lds, const Gemm g, const Sched& S, const Epi& E) {
;     ...
;         E(acc, cur, wr, wc, fr, fq); S.done(cur);
;         if (!has_next) break;
;     __device__ __forceinline__ void operator()(const f32x4 (&acc)[2][2][4][2], const pg8::Unit& u, int wr, int wc, int fr, int fq) const {
;     ...
;         for (int ai = 0; ai < 2; ++ai)
; #pragma unroll
;             for (int m = 0; m < 4; ++m) { const int row = row0 + ai * 128 + m * 16;
;                 const float* ip; float* op; int b;
;                 if (row < ML_ROWS) { b = row >> 11; ip = xi + (size_t)row * D; op = xo + (size_t)row * D; }
;                 else { b = 8; ip = ci + (size_t)(row - ML_ROWS) * D; op = co + (size_t)(row - ML_ROWS) * D; }
;                 const float* gp = mod + (size_t)b * 12288 + slot * 2048;
; #pragma unroll
;                 for (int bj = 0; bj < 2; ++bj)
; #pragma unroll
;                     for (int n = 0; n < 2; ++n) { const int c = col0 + bj * 128 + n * 16;
;                         const f32x4 r = *(const f32x4*)(ip + c), g = *(const f32x4*)(gp + c);
;                         *(f32x4*)(op + c) = r + g * acc[ai][bj][m][n]; } }
	v_pk_fma_f32 v[110:111], v[110:111], v[146:147], v[178:179]
	v_pk_fma_f32 v[112:113], v[112:113], v[148:149], v[180:181]
	v_pk_fma_f32 v[106:107], v[106:107], v[150:151], v[182:183]
	v_pk_fma_f32 v[108:109], v[108:109], v[152:153], v[184:185]
	v_pk_fma_f32 v[102:103], v[102:103], v[154:155], v[186:187]
	v_pk_fma_f32 v[104:105], v[104:105], v[156:157], v[188:189]
	v_pk_fma_f32 v[98:99], v[98:99], v[158:159], v[190:191]
	v_pk_fma_f32 v[100:101], v[100:101], v[160:161], v[192:193]
	global_store_dwordx4 v142, v[110:113], s[20:21]
	global_store_dwordx4 v142, v[106:109], s[20:21] offset:64
	global_store_dwordx4 v142, v[102:105], s[20:21] offset:512
	global_store_dwordx4 v142, v[98:101], s[20:21] offset:576
	global_load_dwordx4 v[178:181], v145, s[20:21]
	global_load_dwordx4 v[182:185], v145, s[20:21] offset:64
	global_load_dwordx4 v[186:189], v145, s[20:21] offset:512
	global_load_dwordx4 v[190:193], v145, s[20:21] offset:576
	s_waitcnt vmcnt(16)
	v_pk_fma_f32 v[94:95], v[94:95], v[146:147], v[194:195]
	v_pk_fma_f32 v[96:97], v[96:97], v[148:149], v[196:197]
	v_pk_fma_f32 v[90:91], v[90:91], v[150:151], v[198:199]
	v_pk_fma_f32 v[92:93], v[92:93], v[152:153], v[200:201]
	v_pk_fma_f32 v[86:87], v[86:87], v[154:155], v[202:203]
	v_pk_fma_f32 v[88:89], v[88:89], v[156:157], v[204:205]
	v_pk_fma_f32 v[82:83], v[82:83], v[158:159], v[206:207]
	v_pk_fma_f32 v[84:85], v[84:85], v[160:161], v[208:209]
	global_store_dwordx4 v143, v[94:97], s[20:21]
	global_store_dwordx4 v143, v[90:93], s[20:21] offset:64
	global_store_dwordx4 v143, v[86:89], s[20:21] offset:512
	global_store_dwordx4 v143, v[82:85], s[20:21] offset:576
	global_load_dwordx4 v[194:197], v210, s[20:21]
	global_load_dwordx4 v[198:201], v210, s[20:21] offset:64
	global_load_dwordx4 v[202:205], v210, s[20:21] offset:512
	global_load_dwordx4 v[206:209], v210, s[20:21] offset:576
	s_waitcnt vmcnt(16)
	v_pk_fma_f32 v[78:79], v[78:79], v[146:147], v[162:163]
	v_pk_fma_f32 v[80:81], v[80:81], v[148:149], v[164:165]
	v_pk_fma_f32 v[74:75], v[74:75], v[150:151], v[166:167]
	v_pk_fma_f32 v[76:77], v[76:77], v[152:153], v[168:169]
	v_pk_fma_f32 v[70:71], v[70:71], v[154:155], v[170:171]
	v_pk_fma_f32 v[72:73], v[72:73], v[156:157], v[172:173]
	v_pk_fma_f32 v[66:67], v[66:67], v[158:159], v[174:175]
	v_pk_fma_f32 v[68:69], v[68:69], v[160:161], v[176:177]
	global_store_dwordx4 v144, v[78:81], s[20:21]
	global_store_dwordx4 v144, v[74:77], s[20:21] offset:64
	global_store_dwordx4 v144, v[70:73], s[20:21] offset:512
	global_store_dwordx4 v144, v[66:69], s[20:21] offset:576
	global_load_dwordx4 v[162:165], v211, s[20:21]
	global_load_dwordx4 v[166:169], v211, s[20:21] offset:64
	global_load_dwordx4 v[170:173], v211, s[20:21] offset:512
	global_load_dwordx4 v[174:177], v211, s[20:21] offset:576
	s_waitcnt vmcnt(16)
	v_pk_fma_f32 v[62:63], v[62:63], v[146:147], v[178:179]
	v_pk_fma_f32 v[64:65], v[64:65], v[148:149], v[180:181]
	v_pk_fma_f32 v[58:59], v[58:59], v[150:151], v[182:183]
	v_pk_fma_f32 v[60:61], v[60:61], v[152:153], v[184:185]
	v_pk_fma_f32 v[54:55], v[54:55], v[154:155], v[186:187]
	v_pk_fma_f32 v[56:57], v[56:57], v[156:157], v[188:189]
	v_pk_fma_f32 v[50:51], v[50:51], v[158:159], v[190:191]
	v_pk_fma_f32 v[52:53], v[52:53], v[160:161], v[192:193]
	global_store_dwordx4 v145, v[62:65], s[20:21]
	global_store_dwordx4 v145, v[58:61], s[20:21] offset:64
	global_store_dwordx4 v145, v[54:57], s[20:21] offset:512
	global_store_dwordx4 v145, v[50:53], s[20:21] offset:576
	global_load_dwordx4 v[178:181], v137, s[20:21]
	global_load_dwordx4 v[182:185], v137, s[20:21] offset:64
	global_load_dwordx4 v[186:189], v137, s[20:21] offset:512
	global_load_dwordx4 v[190:193], v137, s[20:21] offset:576
	s_waitcnt vmcnt(16)
	v_pk_fma_f32 v[46:47], v[46:47], v[146:147], v[194:195]
	v_pk_fma_f32 v[48:49], v[48:49], v[148:149], v[196:197]
	v_pk_fma_f32 v[42:43], v[42:43], v[150:151], v[198:199]
	v_pk_fma_f32 v[44:45], v[44:45], v[152:153], v[200:201]
	v_pk_fma_f32 v[38:39], v[38:39], v[154:155], v[202:203]
	v_pk_fma_f32 v[40:41], v[40:41], v[156:157], v[204:205]
	v_pk_fma_f32 v[34:35], v[34:35], v[158:159], v[206:207]
	v_pk_fma_f32 v[36:37], v[36:37], v[160:161], v[208:209]
	global_store_dwordx4 v210, v[46:49], s[20:21]
	global_store_dwordx4 v210, v[42:45], s[20:21] offset:64
	global_store_dwordx4 v210, v[38:41], s[20:21] offset:512
	global_store_dwordx4 v210, v[34:37], s[20:21] offset:576
	s_waitcnt vmcnt(12)
	v_pk_fma_f32 v[30:31], v[30:31], v[146:147], v[162:163]
	v_pk_fma_f32 v[32:33], v[32:33], v[148:149], v[164:165]
	v_pk_fma_f32 v[26:27], v[26:27], v[150:151], v[166:167]
	v_pk_fma_f32 v[28:29], v[28:29], v[152:153], v[168:169]
	v_pk_fma_f32 v[22:23], v[22:23], v[154:155], v[170:171]
	v_pk_fma_f32 v[24:25], v[24:25], v[156:157], v[172:173]
	v_pk_fma_f32 v[18:19], v[18:19], v[158:159], v[174:175]
	v_pk_fma_f32 v[20:21], v[20:21], v[160:161], v[176:177]
	global_store_dwordx4 v211, v[30:33], s[20:21]
	global_store_dwordx4 v211, v[26:29], s[20:21] offset:64
	global_store_dwordx4 v211, v[22:25], s[20:21] offset:512
	global_store_dwordx4 v211, v[18:21], s[20:21] offset:576
	s_waitcnt vmcnt(8)
	v_pk_fma_f32 v[14:15], v[14:15], v[146:147], v[178:179]
	v_pk_fma_f32 v[16:17], v[16:17], v[148:149], v[180:181]
	v_pk_fma_f32 v[10:11], v[10:11], v[150:151], v[182:183]
	v_pk_fma_f32 v[12:13], v[12:13], v[152:153], v[184:185]
	v_pk_fma_f32 v[6:7], v[6:7], v[154:155], v[186:187]
	v_pk_fma_f32 v[8:9], v[8:9], v[156:157], v[188:189]
	v_pk_fma_f32 v[2:3], v[2:3], v[158:159], v[190:191]
	v_pk_fma_f32 v[4:5], v[4:5], v[160:161], v[192:193]
	global_store_dwordx4 v137, v[14:17], s[20:21]
	global_store_dwordx4 v137, v[10:13], s[20:21] offset:64
	global_store_dwordx4 v137, v[6:9], s[20:21] offset:512
	global_store_dwordx4 v137, v[2:5], s[20:21] offset:576
	s_mov_b64 s[18:19], s[10:11]
	s_mov_b64 s[16:17], s[8:9]
	s_and_b64 vcc, exec, s[0:1]
	s_cbranch_vccz .LBB0_1340
	s_waitcnt vmcnt(0)
	s_cmpk_gt_u32 s24, 0xff
	s_cbranch_scc1 .LBB0_1347
	s_barrier
